# attention K/V LDS tiles bank-conflict free: XOR chunk swizzle on K rows, odd V rows shifted into the pad
# speedup vs baseline: 1.0456x; 1.0064x over previous
; #define LAS __attribute__((address_space(3)))
; __device__ __forceinline__ void attn_stage(LAS unsigned char* buf, int tid, u32x4 rk, u32x4 rv, u32x4 rr) {
;   LAS bf16_t* Ks = (LAS bf16_t*)buf; LAS bf16_t* Vs = (LAS bf16_t*)(buf + 64 * AT_KSTR * 2);
;   const int skey = tid >> 3, sch = tid & 7;
;   *(LAS u32x4*)(Ks + skey * AT_KSTR + sch * 8) = rk;
;   if (tid < 256) { const int rkey = tid >> 2, rch = tid & 3; *(LAS u32x4*)(Ks + rkey * AT_KSTR + 64 + rch * 8) = rr; }
;   *(LAS u32x4*)(Vs + skey * AT_VSTR + sch * 8) = rv;
; }
; __device__ __forceinline__ void attn_unit(LAS unsigned char* lds, const bf16_t* Q, const bf16_t* KV, const bf16_t* KR, bf16_t* MIX, size_t qrow0, size_t krow0, int ntiles, int h, const int tid) {
;   const int lane = tid & 63, wid = tid >> 6, c16 = lane & 15, quad = lane >> 4, tq = (lane & 15) >> 2, tp = lane & 3;
;   const bf16_t* gk = KV + (krow0 + (tid >> 3)) * 1024 + h * 128 + (tid & 7) * 8;
;   const bf16_t* gr = KR + (krow0 + ((tid & 255) >> 2)) * 32 + (tid & 3) * 8;
;     ...
;     const LAS bf16_t* Ks = (const LAS bf16_t*)buf; const LAS bf16_t* Vs = (const LAS bf16_t*)(buf + 64 * AT_KSTR * 2);
;     f32x4 s[4][2];
; #pragma unroll
;     for (int kb = 0; kb < 4; ++kb) {
;       bf16x8 kf[3];
; #pragma unroll
;       for (int ks = 0; ks < 3; ++ks) kf[ks] = *(const LAS bf16x8*)(Ks + (kb * 16 + c16) * AT_KSTR + ks * 32 + quad * 8);
.LBB0_367:
	s_and_b64 vcc, exec, s[0:1]
	s_cbranch_vccz .LBB0_669
	s_mov_b64 s[0:1], -1
	s_mov_b64 s[6:7], 0
	s_cmp_lt_i32 s61, 3
	s_mov_b64 s[8:9], 0
	s_cbranch_scc1 .LBB0_548
	s_cmp_gt_i32 s61, 3
	s_cbranch_scc0 .LBB0_429
	s_cmp_eq_u32 s61, 4
	s_mov_b64 s[8:9], -1
	s_cbranch_scc0 .LBB0_428
	v_readlane_b32 s0, v253, 23
	s_cmpk_gt_i32 s0, 0x7ff
	s_movk_i32 s0, 0x100
	s_waitcnt vmcnt(2)
	v_and_b32_e32 v144, 15, v194
	v_bfe_u32 v0, v194, 4, 2
	v_ashrrev_i32_e32 v112, 3, v194
	v_lshlrev_b32_e32 v2, 3, v194
	v_lshrrev_b32_e32 v3, 2, v194
	v_ashrrev_i32_e32 v4, 1, v194
	v_bfe_u32 v5, v194, 2, 2
	v_cmp_gt_i32_e64 s[42:43], s0, v194
	s_movk_i32 s0, 0xd0
	v_bfe_u32 v145, v194, 2, 6
	v_ashrrev_i32_e32 v113, 31, v112
	v_and_b32_e32 v122, 56, v2
	v_and_b32_e32 v123, 24, v2
	v_and_b32_e32 v114, 0xffffffe0, v4
	v_lshlrev_b32_e32 v120, 3, v0
	v_lshlrev_b32_e32 v124, 4, v0
	v_mul_lo_u32 v148, v112, s0
	v_mul_lo_u32 v149, v3, s0
	v_lshlrev_b32_e32 v150, 6, v112
	v_lshl_or_b32 v147, v0, 2, v5
	v_mul_u32_u24_e32 v146, 0xd0, v144
	v_add_u32_e32 v234, 4, v144
	v_bfe_u32 v234, v234, 3, 1
	v_sub_u32_e32 v234, 0, v234
	v_bfe_u32 v235, v194, 4, 1
	v_lshlrev_b32_e32 v235, 5, v235
	v_sub_u32_e32 v235, 16, v235
	v_and_b32_e32 v234, v234, v235
	v_add_u32_e32 v146, v146, v234
	v_and_b32_e32 v235, 1, v194
	v_lshlrev_b32_e32 v235, 5, v235
	v_sub_u32_e32 v235, 16, v235
	v_bfe_u32 v183, v194, 3, 4
	v_add_u32_e32 v183, 4, v183
	v_bfe_u32 v183, v183, 3, 1
	v_sub_u32_e32 v183, 0, v183
	v_and_b32_e32 v183, v183, v235
	v_add_u32_e32 v148, v148, v183
	v_bfe_u32 v234, v194, 2, 4
	v_add_u32_e32 v234, 4, v234
	v_bfe_u32 v234, v234, 3, 1
	v_sub_u32_e32 v234, 0, v234
	v_and_b32_e32 v234, v234, v235
	v_add_u32_e32 v149, v149, v234
	v_bfe_u32 v184, v194, 3, 1
	v_lshlrev_b32_e32 v184, 4, v184
	v_bfe_u32 v185, v194, 2, 1
	v_lshlrev_b32_e32 v185, 4, v185
	s_cbranch_scc1 .LBB0_396
	v_ashrrev_i32_e32 v115, 31, v114
	v_or_b32_e32 v0, 0x100, v144
	v_lshl_add_u64 v[116:117], v[0:1], 0, v[114:115]
	v_readlane_b32 s0, v252, 39
	v_lshlrev_b32_e32 v126, 1, v123
	v_lshlrev_b32_e32 v0, 1, v122
	v_mov_b32_e32 v125, v1
	v_readlane_b32 s1, v252, 40
	v_add3_u32 v115, 0, v148, v0
	v_add_u32_e32 v0, 0, v126
	v_and_b32_e32 v2, 64, v225
	v_lshl_add_u64 v[118:119], s[0:1], 0, v[124:125]
	v_add_u32_e32 v125, v0, v149
	v_xor_b32_e32 v0, 16, v225
	v_add_u32_e32 v2, 64, v2
	v_cmp_lt_i32_e32 vcc, v0, v2
	v_readlane_b32 s0, v252, 43
	v_mov_b32_e32 v127, v1
	v_cndmask_b32_e32 v0, v225, v0, vcc
	v_lshlrev_b32_e32 v152, 2, v0
	v_xor_b32_e32 v0, 32, v225
	v_cmp_lt_i32_e32 vcc, v0, v2
	v_readlane_b32 s1, v252, 44
	v_lshlrev_b64 v[2:3], 11, v[112:113]
	v_cndmask_b32_e32 v0, v225, v0, vcc
	v_lshl_add_u64 v[128:129], s[0:1], 0, v[126:127]
	s_movk_i32 s0, 0x90
	v_lshlrev_b32_e32 v153, 2, v0
	v_lshlrev_b32_e32 v0, 2, v194
	v_mul_lo_u32 v127, v112, s0
	v_sub_u32_e32 v127, v127, v184
	v_and_b32_e32 v154, 12, v0
	v_and_b32_e32 v0, 3, v194
	v_readlane_b32 s0, v252, 60
	v_lshlrev_b32_e32 v0, 4, v0
	v_readlane_b32 s1, v252, 61
	v_mov_b32_e32 v121, v1
	v_add_u32_e32 v4, 0, v124
	v_lshl_add_u64 v[132:133], s[0:1], 0, v[0:1]
	v_and_b32_e32 v0, 7, v194
	v_readlane_b32 s0, v252, 62
	v_lshl_add_u32 v5, v154, 1, 0
	v_mul_u32_u24_e32 v155, 0x90, v147
	v_sub_u32_e32 v155, v155, v185
	v_lshl_or_b32 v2, v0, 4, v2
	v_readlane_b32 s1, v252, 63
	v_readlane_b32 s9, v253, 23
	v_sub_u32_e32 v151, v115, v150
	v_sub_u32_e32 v151, v151, v183
	v_sub_u32_e32 v151, v151, v184
	v_lshl_add_u64 v[130:131], s[84:85], 0, v[120:121]
	v_lshlrev_b32_e32 v121, 6, v145
	v_lshl_add_u64 v[134:135], s[0:1], 0, v[2:3]
	v_add_u32_e32 v156, v4, v146
	v_add_u32_e32 v157, v5, v155
	s_mov_b32 s8, s9
	s_branch .LBB0_374

; #define LAS __attribute__((address_space(3)))
; __device__ __forceinline__ void attn_unit(LAS unsigned char* lds, const bf16_t* Q, const bf16_t* KV, const bf16_t* KR, bf16_t* MIX, size_t qrow0, size_t krow0, int ntiles, int h, const int tid) {
;   const int lane = tid & 63, wid = tid >> 6, c16 = lane & 15, quad = lane >> 4, tq = (lane & 15) >> 2, tp = lane & 3;
;   const bf16_t* gk = KV + (krow0 + (tid >> 3)) * 1024 + h * 128 + (tid & 7) * 8;
;   const bf16_t* gr = KR + (krow0 + ((tid & 255) >> 2)) * 32 + (tid & 3) * 8;
;   bf16x8 qf[2][3];
; __device__ __forceinline__ void attn_phase(const Params& p, LAS unsigned char* lds, const int tid, const int bid) {
;     ...
;   for (int u = bid; u < 64; u += G) {
;     const int b = u & 7, h = u >> 3;
;     attn_unit(lds, Q, KV, KR, MIX, (size_t)b * SEGL, (size_t)b * SEGL, CTXL / 64, h, tid);
.LBB0_396:
	v_readlane_b32 s0, v253, 23
	s_cmp_gt_i32 s0, 63
	s_cbranch_scc1 .LBB0_427
	v_readlane_b32 s0, v252, 39
	v_mov_b32_e32 v125, v1
	v_readlane_b32 s1, v252, 40
	v_lshlrev_b32_e32 v0, 1, v123
	v_lshlrev_b32_e32 v2, 1, v122
	v_lshl_add_u64 v[116:117], s[0:1], 0, v[124:125]
	v_readlane_b32 s0, v252, 43
	v_readlane_b32 s1, v252, 44
	v_add3_u32 v130, 0, v148, v2
	v_and_b32_e32 v2, 64, v225
	v_lshl_add_u64 v[118:119], s[0:1], 0, v[0:1]
	v_add_u32_e32 v0, 0, v0
	v_add_u32_e32 v131, v0, v149
	v_xor_b32_e32 v0, 16, v225
	v_add_u32_e32 v2, 64, v2
	v_cmp_lt_i32_e32 vcc, v0, v2
	v_mov_b32_e32 v121, v1
	s_movk_i32 s0, 0x100
	v_cndmask_b32_e32 v0, v225, v0, vcc
	v_lshlrev_b32_e32 v133, 2, v0
	v_xor_b32_e32 v0, 32, v225
	v_cmp_lt_i32_e32 vcc, v0, v2
	v_add_u32_e32 v2, 0, v123
	v_mul_u32_u24_e32 v3, 0x90, v147
	v_sub_u32_e32 v3, v3, v185
	v_cndmask_b32_e32 v0, v225, v0, vcc
	v_lshlrev_b32_e32 v134, 2, v0
	v_add_u32_e32 v0, 0, v124
	v_ashrrev_i32_e32 v115, 31, v114
	v_cmp_gt_i32_e64 s[42:43], s0, v194
	v_sub_u32_e32 v132, v130, v150
	v_sub_u32_e32 v132, v132, v183
	v_sub_u32_e32 v132, v132, v184
	v_lshl_add_u64 v[120:121], s[84:85], 0, v[120:121]
	v_lshlrev_b32_e32 v122, 1, v122
	v_add_u32_e32 v135, v0, v146
	v_add_u32_e32 v136, v2, v3
	v_readlane_b32 s4, v253, 23
	s_branch .LBB0_399
